# e44 + rmsnorm rows wait only for the 192 adaLN GEMV workgroups (write-through outputs + counter) instead of the full P0->P1 barrier; guard before P1->P2 arrival
# speedup vs baseline: 1.0089x; 1.0089x over previous
; __device__ __forceinline__ void gemv_item(LAS float* L, int item, const float* c, const float* c_ctx, const float* ada_w, const float* ada_b, float* mod) {
;     ...
;     __syncthreads();
;     if (tid < 96) { float sum = 0.f;
; #pragma unroll
;         for (int w = 0; w < 8; ++w) sum += red[w * 96 + tid];
;         const int r = tid >> 5, col = tid & 31; mod[r * 3 * D + n0 + col] = sum + ada_b[n0 + col]; }
.LBB0_75:
	s_or_b64 exec, exec, s[6:7]
	s_movk_i32 s0, 0x60
	v_cmp_gt_u32_e32 vcc, s0, v0
	s_waitcnt lgkmcnt(0)
	s_barrier
	s_and_saveexec_b64 s[6:7], vcc
	s_cbranch_execz .LBB0_77
	v_readlane_b32 s56, v254, 2
	v_readlane_b32 s66, v254, 12
	v_readlane_b32 s67, v254, 13
	v_and_b32_e32 v1, 31, v0
	s_mov_b64 s[18:19], s[66:67]
	v_or_b32_e32 v4, s4, v1
	v_mov_b32_e32 v2, s18
	v_mov_b32_e32 v3, s19
	v_ashrrev_i32_e32 v5, 31, v4
	v_lshl_add_u64 v[2:3], v[4:5], 2, v[2:3]
	global_load_dword v12, v[2:3], off
	v_lshl_add_u32 v2, v0, 2, 0
	v_lshrrev_b32_e32 v3, 5, v0
	s_movk_i32 s0, 0x1800
	v_mov_b32_e32 v4, s4
	v_add_u32_e32 v5, 0x6000, v2
	v_add_u32_e32 v6, 0x6200, v2
	v_add_u32_e32 v7, 0x6400, v2
	v_add_u32_e32 v8, 0x6800, v2
	v_mad_u32_u24 v10, v3, s0, v4
	ds_read2_b32 v[2:3], v5 offset1:96
	ds_read2_b32 v[4:5], v6 offset0:64 offset1:160
	ds_read2_b32 v[6:7], v7 offset0:128 offset1:224
	ds_read2_b32 v[8:9], v8 offset0:64 offset1:160
	v_or_b32_e32 v10, v10, v1
	s_waitcnt lgkmcnt(3)
	v_add_f32_e32 v1, 0, v2
	v_add_f32_e32 v1, v1, v3
	s_waitcnt lgkmcnt(2)
	v_add_f32_e32 v1, v1, v4
	v_add_f32_e32 v1, v1, v5
	s_waitcnt lgkmcnt(1)
	v_add_f32_e32 v1, v1, v6
	v_ashrrev_i32_e32 v11, 31, v10
	v_add_f32_e32 v1, v1, v7
	v_lshl_add_u64 v[10:11], v[10:11], 2, s[50:51]
	s_waitcnt lgkmcnt(0)
	v_add_f32_e32 v1, v1, v8
	v_add_co_u32_e32 v10, vcc, 0x100000, v10
	v_add_f32_e32 v1, v1, v9
	s_nop 0
	v_addc_co_u32_e32 v11, vcc, 0, v11, vcc
	v_readlane_b32 s57, v254, 3
	v_readlane_b32 s58, v254, 4
	v_readlane_b32 s59, v254, 5
	v_readlane_b32 s60, v254, 6
	v_readlane_b32 s61, v254, 7
	v_readlane_b32 s62, v254, 8
	v_readlane_b32 s63, v254, 9
	v_readlane_b32 s64, v254, 10
	v_readlane_b32 s65, v254, 11
	v_readlane_b32 s68, v254, 14
	v_readlane_b32 s69, v254, 15
	v_readlane_b32 s70, v254, 16
	v_readlane_b32 s71, v254, 17
	s_waitcnt vmcnt(0)
	v_add_f32_e32 v1, v1, v12
	global_store_dword v[10:11], v1, off sc0 sc1

; __device__ __forceinline__ void xcd_barrier(const XcdBarrier& b) {
;     asm volatile("s_waitcnt vmcnt(0)" ::: "memory");
;     __syncthreads();
;     if (threadIdx.x == 0) {
;         unsigned* bar = b.bar;
;         __builtin_amdgcn_s_waitcnt(0);
;         unsigned nloc = b.st[0], nx = b.st[1];
;         if (nloc == 0u) { xcd_barrier_complete(bar, b.x, nloc, nx); b.st[0] = nloc; b.st[1] = nx; }
.LBB0_78:
	s_cmp_gt_i32 s79, 1
	s_cselect_b64 s[4:5], -1, 0
	s_and_b64 s[0:1], s[2:3], s[4:5]
	s_andn2_b64 vcc, exec, s[0:1]
	s_cbranch_vccnz .LBB0_132
	s_waitcnt vmcnt(0)
	s_barrier
	s_and_saveexec_b64 s[2:3], s[82:83]
	s_cbranch_execz .LBB0_131
	s_cmpk_gt_i32 s16, 0xbf
	s_cbranch_scc1 .Lp0_gcnt_skip
	v_mov_b32_e32 v1, 0xe000
	v_mov_b32_e32 v3, 1
	global_atomic_add v1, v3, s[50:51]
.Lp0_gcnt_skip:
	s_add_i32 s0, 0, 0x23000
	v_mov_b32_e32 v1, s0
	s_waitcnt vmcnt(0) expcnt(0) lgkmcnt(0)
	ds_read_b32 v3, v1
	s_add_i32 s0, 0, 0x23004
	v_mov_b32_e32 v1, s0
	ds_read_b32 v1, v1
	s_waitcnt lgkmcnt(1)
	v_cmp_ne_u32_e32 vcc, 0, v3
	s_cbranch_vccnz .LBB0_95
	v_readlane_b32 s6, v254, 0
	v_readlane_b32 s7, v254, 1
	s_load_dwordx2 s[0:1], s[6:7], 0x4
	s_add_u32 s6, s50, 0x1000
	s_addc_u32 s7, s51, 0
	s_add_u32 s8, s50, 0x1100
	s_addc_u32 s9, s51, 0
	s_add_u32 s10, s50, 0x1200
	s_addc_u32 s11, s51, 0
	s_waitcnt lgkmcnt(0)
	s_mul_i32 s0, s0, s17
	s_add_u32 s12, s50, 0x1300
	s_mul_i32 s0, s0, s1
	s_addc_u32 s13, s51, 0
	s_mov_b32 s1, 1
	v_mov_b32_e32 v17, 0
	s_branch .LBB0_83

; #define SUB(i, ...) do { if (PROBE_PH == phk && PROBE_SUB == (i)) { __syncthreads(); tp0 = __builtin_amdgcn_s_memrealtime(); } __VA_ARGS__ if (PROBE_PH == phk && PROBE_SUB == (i)) { asm volatile("s_waitcnt vmcnt(0)" ::: "memory"); __syncthreads(); tp1 = __builtin_amdgcn_s_memrealtime(); } } while (0)
; __global__ void __launch_bounds__(NTHREADS, 2) mk_fwd(Args a) {
;     ...
;         { pg8::ListOrder S; S.init(32, 1, 8, G, vcu >= 128 && vcu < 160 ? vcu - 128 : 1 << 20);
;           EpiWp E{(f16*)(a.ws + WS_WIN)};
;           SUB(3, pg8::gemm_phase<CfgWp, EpiWp, pg8::ListOrder, true, true>(lds, (const char*)(a.ws + WS_WPOOL), (const char*)(a.ws + WS_WRAW), S, E); ); }
;         SUB(1, norm_rows(vcu * NWAVES + wave, lane, a.in[0], a.in[2], a.in[6], (const float*)(a.ws + WS_MOD), (f16*)(a.ws + WS_H)); );
.LBB0_165:
	s_and_saveexec_b64 s[2:3], s[82:83]
	s_cbranch_execz .Lp1_waited
	s_and_b32 s98, s81, 0xffffffe0
	s_cmpk_eq_i32 s98, 0x80
	s_mov_b32 s98, 0xe000
	s_movk_i32 s101, 0xc0
	s_cbranch_scc0 .Lp1_wsel
	s_movk_i32 s98, 0x3500
	s_movk_i32 s101, 1
.Lp1_wsel:
	v_mov_b32_e32 v2, s98
	s_mov_b32 s0, 0

; __device__ __forceinline__ void xcd_barrier(const XcdBarrier& b) {
;     asm volatile("s_waitcnt vmcnt(0)" ::: "memory");
;     __syncthreads();
;     if (threadIdx.x == 0) {
;         unsigned* bar = b.bar;
;         __builtin_amdgcn_s_waitcnt(0);
;         unsigned nloc = b.st[0], nx = b.st[1];
;         if (nloc == 0u) { xcd_barrier_complete(bar, b.x, nloc, nx); b.st[0] = nloc; b.st[1] = nx; }
.Lp1_seam:
	s_and_saveexec_b64 s[0:1], s[82:83]
	s_cbranch_execz .Lp1_g_done
	v_mov_b32_e32 v2, 0x3500
	s_mov_b32 s4, 0
.Lp1_g:
	global_load_dword v3, v2, s[50:51] sc1
	s_add_u32 s4, s4, 1
	s_waitcnt vmcnt(0)
	v_readfirstlane_b32 s5, v3
	s_cmp_lg_u32 s5, 0
	s_cbranch_scc1 .Lp1_g_done
	s_cmp_gt_u32 s4, 0x4000
	s_cbranch_scc1 .Lp1_g_done
	s_sleep 1
	s_branch .Lp1_g
.Lp1_g_done:
	s_or_b64 exec, exec, s[0:1]
	s_cmp_gt_i32 s79, 2
	s_cselect_b64 s[2:3], -1, 0
	s_and_b64 s[0:1], s[76:77], s[2:3]
	s_andn2_b64 vcc, exec, s[0:1]
	s_cbranch_vccnz .LBB0_284
	s_waitcnt vmcnt(0)
	s_waitcnt vmcnt(0)
	s_barrier
	s_and_saveexec_b64 s[4:5], s[82:83]
	s_cbranch_execz .LBB0_283
	s_add_i32 s0, 0, 0x23000
	v_mov_b32_e32 v1, s0
	s_waitcnt vmcnt(0) expcnt(0) lgkmcnt(0)
	ds_read_b32 v3, v1
	s_add_i32 s0, 0, 0x23004
	v_mov_b32_e32 v1, s0
	ds_read_b32 v1, v1
	s_waitcnt lgkmcnt(1)
	v_cmp_ne_u32_e32 vcc, 0, v3
	s_cbranch_vccnz .LBB0_247
	v_readlane_b32 s6, v254, 0
	v_readlane_b32 s7, v254, 1
	s_load_dwordx2 s[0:1], s[6:7], 0x4
	s_add_u32 s6, s50, 0x1000
	s_addc_u32 s7, s51, 0
	s_add_u32 s8, s50, 0x1100
	s_addc_u32 s9, s51, 0
	s_add_u32 s10, s50, 0x1200
	s_addc_u32 s11, s51, 0
	s_waitcnt lgkmcnt(0)
	s_mul_i32 s0, s0, s17
	s_add_u32 s12, s50, 0x1300
	s_mul_i32 s0, s0, s1
	s_addc_u32 s13, s51, 0
	s_mov_b32 s1, 1
	v_mov_b32_e32 v17, 0
	s_branch .LBB0_235
